# speedup vs baseline: 1.0052x; 1.0052x over previous
; __device__ __forceinline__ unsigned cvt_pk_bf16(float lo, float hi) { unsigned r; asm volatile("v_cvt_pk_bf16_f32 %0, %1, %2" : "=v"(r) : "v"(lo), "v"(hi)); return r; }
;     __device__ __forceinline__ void operator()(const f32x4 (&acc)[2][2][4][2], const Unit& u, int wr, int wc, int fr, int fq) const {
;     ...
;             for (int m = 0; m < 4; ++m) { const int row = row0 + ai * HALF + m * 16; const float rs = __builtin_amdgcn_rsqf((float)sq[ai][m] * (1.0f / (1024.0f * 1048576.0f)) + RMS_EPS) * sc;
;     __device__ __forceinline__ void operator()(const f32x4 (&acc)[2][2][4][2], const Unit& u, int wr, int wc, int fr, int fq) const {
;         const int row0 = u.pm * BM + wr * 64 + fr; const int col0 = u.pn * HALF + wc * 32 + 8 * fq;
;         unsigned long long sq[2][4];
; #pragma unroll
;         for (int ai = 0; ai < 2; ++ai)
; #pragma unroll
;             for (int m = 0; m < 4; ++m) sq[ai][m] = ssq[row0 + ai * HALF + m * 16];
; #pragma unroll
;         for (int ai = 0; ai < 2; ++ai)
; #pragma unroll
;             for (int m = 0; m < 4; ++m) { const int row = row0 + ai * HALF + m * 16; const float rs = __builtin_amdgcn_rsqf((float)sq[ai][m] * (1.0f / (1024.0f * 1048576.0f)) + RMS_EPS);
;                 float hv[8];
; #pragma unroll
;                 for (int n = 0; n < 2; ++n)
; #pragma unroll
;                     for (int j = 0; j < 4; ++j) { const float g = acc[ai][0][m][n][j] * rs, uu = acc[ai][1][m][n][j] * rs;
;                         const float sg = g * __builtin_amdgcn_rcpf(1.0f + __builtin_amdgcn_exp2f(-1.4426950408889634f * g)); hv[n * 4 + j] = sg * uu; }
;                 u32x4 w; w.x = cvt_pk_bf16(hv[0], hv[1]); w.y = cvt_pk_bf16(hv[2], hv[3]); w.z = cvt_pk_bf16(hv[4], hv[5]); w.w = cvt_pk_bf16(hv[6], hv[7]);
;                 *(u32x4*)(H + (size_t)row * 2816 + col0) = w; }
.LBB0_431:
	v_lshl_add_u32 v160, s16, 8, v165
	v_ashrrev_i32_e32 v161, 31, v160
	v_lshl_add_u64 v[140:141], v[160:161], 3, s[34:35]
	global_load_dwordx2 v[170:171], v[140:141], off
	global_load_dwordx2 v[146:147], v[140:141], off offset:1024
	global_load_dwordx2 v[144:145], v[140:141], off offset:1152
	v_or_b32_e32 v156, 16, v160
	v_ashrrev_i32_e32 v157, 31, v156
	v_or_b32_e32 v152, 32, v160
	v_lshl_add_u64 v[142:143], v[156:157], 3, s[34:35]
	v_ashrrev_i32_e32 v153, 31, v152
	v_or_b32_e32 v148, 48, v160
	global_load_dwordx2 v[158:159], v[142:143], off
	v_lshl_add_u64 v[142:143], v[152:153], 3, s[34:35]
	v_ashrrev_i32_e32 v149, 31, v148
	global_load_dwordx2 v[154:155], v[142:143], off
	v_lshl_add_u64 v[142:143], v[148:149], 3, s[34:35]
	global_load_dwordx2 v[150:151], v[142:143], off
	v_lshl_or_b32 v162, s17, 7, v167
	global_load_dwordx2 v[142:143], v[140:141], off offset:1280
	v_ashrrev_i32_e32 v163, 31, v162
	global_load_dwordx2 v[140:141], v[140:141], off offset:1408
	s_movk_i32 s9, 0x1600
	v_add_u32_e32 v161, 0x80, v160
	v_add_u32_e32 v157, 0x90, v160
	v_add_u32_e32 v153, 0xa0, v160
	v_add_u32_e32 v149, 0xb0, v160
	s_andn2_b64 vcc, exec, s[4:5]
	s_waitcnt vmcnt(0)
	v_ffbh_u32_e32 v212, v171
	v_ffbh_u32_e32 v213, v159
	v_ffbh_u32_e32 v214, v155
	v_ffbh_u32_e32 v215, v151
	v_ffbh_u32_e32 v216, v147
	v_ffbh_u32_e32 v217, v145
	v_ffbh_u32_e32 v218, v143
	v_ffbh_u32_e32 v219, v141
	v_min_u32_e32 v212, 32, v212
	v_min_u32_e32 v213, 32, v213
	v_min_u32_e32 v214, 32, v214
	v_min_u32_e32 v215, 32, v215
	v_min_u32_e32 v216, 32, v216
	v_min_u32_e32 v217, 32, v217
	v_min_u32_e32 v218, 32, v218
	v_min_u32_e32 v219, 32, v219
	v_lshlrev_b64 v[196:197], v212, v[170:171]
	v_lshlrev_b64 v[198:199], v213, v[158:159]
	v_lshlrev_b64 v[200:201], v214, v[154:155]
	v_lshlrev_b64 v[202:203], v215, v[150:151]
	v_lshlrev_b64 v[204:205], v216, v[146:147]
	v_lshlrev_b64 v[206:207], v217, v[144:145]
	v_lshlrev_b64 v[208:209], v218, v[142:143]
	v_lshlrev_b64 v[210:211], v219, v[140:141]
	v_min_u32_e32 v196, 1, v196
	v_min_u32_e32 v198, 1, v198
	v_min_u32_e32 v200, 1, v200
	v_min_u32_e32 v202, 1, v202
	v_min_u32_e32 v204, 1, v204
	v_min_u32_e32 v206, 1, v206
	v_min_u32_e32 v208, 1, v208
	v_min_u32_e32 v210, 1, v210
	v_or_b32_e32 v196, v197, v196
	v_or_b32_e32 v198, v199, v198
	v_or_b32_e32 v200, v201, v200
	v_or_b32_e32 v202, v203, v202
	v_or_b32_e32 v204, v205, v204
	v_or_b32_e32 v206, v207, v206
	v_or_b32_e32 v208, v209, v208
	v_or_b32_e32 v210, v211, v210
	v_cvt_f32_u32_e32 v196, v196
	v_cvt_f32_u32_e32 v198, v198
	v_cvt_f32_u32_e32 v200, v200
	v_cvt_f32_u32_e32 v202, v202
	v_cvt_f32_u32_e32 v204, v204
	v_cvt_f32_u32_e32 v206, v206
	v_cvt_f32_u32_e32 v208, v208
	v_cvt_f32_u32_e32 v210, v210
	v_sub_u32_e32 v212, 32, v212
	v_sub_u32_e32 v213, 32, v213
	v_sub_u32_e32 v214, 32, v214
	v_sub_u32_e32 v215, 32, v215
	v_sub_u32_e32 v216, 32, v216
	v_sub_u32_e32 v217, 32, v217
	v_sub_u32_e32 v218, 32, v218
	v_sub_u32_e32 v219, 32, v219
	v_ldexp_f32 v196, v196, v212
	v_ldexp_f32 v198, v198, v213
	v_ldexp_f32 v200, v200, v214
	v_ldexp_f32 v202, v202, v215
	v_ldexp_f32 v204, v204, v216
	v_ldexp_f32 v206, v206, v217
	v_ldexp_f32 v208, v208, v218
	v_ldexp_f32 v210, v210, v219
	v_fmamk_f32 v196, v196, 0x30800000, v240
	v_fmamk_f32 v198, v198, 0x30800000, v240
	v_fmamk_f32 v200, v200, 0x30800000, v240
	v_fmamk_f32 v202, v202, 0x30800000, v240
	v_fmamk_f32 v204, v204, 0x30800000, v240
	v_fmamk_f32 v206, v206, 0x30800000, v240
	v_fmamk_f32 v208, v208, 0x30800000, v240
	v_fmamk_f32 v210, v210, 0x30800000, v240
	v_rsq_f32_e32 v172, v196
	v_rsq_f32_e32 v173, v198
	v_rsq_f32_e32 v174, v200
	v_rsq_f32_e32 v175, v202
	v_rsq_f32_e32 v176, v204
	v_rsq_f32_e32 v177, v206
	v_rsq_f32_e32 v178, v208
	v_rsq_f32_e32 v179, v210
	v_mov_b64_e32 v[180:181], s[56:57]
	v_lshlrev_b64 v[182:183], 1, v[162:163]
	v_mul_f32_e32 v196, v126, v172
	v_mul_f32_e32 v197, v127, v172
	v_mul_f32_e32 v198, v128, v172
	v_mul_f32_e32 v199, v129, v172
	v_mul_f32_e32 v200, v118, v172
	v_mul_f32_e32 v201, v119, v172
	v_mul_f32_e32 v202, v120, v172
	v_mul_f32_e32 v203, v121, v172
	v_mul_f32_e32 v204, v122, v172
	v_mul_f32_e32 v205, v123, v172
	v_mul_f32_e32 v206, v124, v172
	v_mul_f32_e32 v207, v125, v172
	v_mul_f32_e32 v208, v114, v172
	v_mul_f32_e32 v209, v115, v172
	v_mul_f32_e32 v210, v116, v172
	v_mul_f32_e32 v211, v117, v172
	v_mul_f32_e32 v212, 0xbfb8aa3b, v196
	v_mul_f32_e32 v213, 0xbfb8aa3b, v197
	v_mul_f32_e32 v214, 0xbfb8aa3b, v198
	v_mul_f32_e32 v215, 0xbfb8aa3b, v199
	v_mul_f32_e32 v216, 0xbfb8aa3b, v200
	v_mul_f32_e32 v217, 0xbfb8aa3b, v201
	v_mul_f32_e32 v218, 0xbfb8aa3b, v202
	v_mul_f32_e32 v219, 0xbfb8aa3b, v203
	v_exp_f32_e32 v212, v212
	v_exp_f32_e32 v213, v213
	v_exp_f32_e32 v214, v214
	v_exp_f32_e32 v215, v215
	v_exp_f32_e32 v216, v216
	v_exp_f32_e32 v217, v217
	v_exp_f32_e32 v218, v218
	v_exp_f32_e32 v219, v219
	v_add_f32_e32 v212, 1.0, v212
	v_add_f32_e32 v213, 1.0, v213
	v_add_f32_e32 v214, 1.0, v214
	v_add_f32_e32 v215, 1.0, v215
	v_add_f32_e32 v216, 1.0, v216
	v_add_f32_e32 v217, 1.0, v217
	v_add_f32_e32 v218, 1.0, v218
	v_add_f32_e32 v219, 1.0, v219
	v_rcp_f32_e32 v212, v212
	v_rcp_f32_e32 v213, v213
	v_rcp_f32_e32 v214, v214
	v_rcp_f32_e32 v215, v215
	v_rcp_f32_e32 v216, v216
	v_rcp_f32_e32 v217, v217
	v_rcp_f32_e32 v218, v218
	v_rcp_f32_e32 v219, v219
	v_mul_f32_e32 v212, v196, v212
	v_mul_f32_e32 v213, v197, v213
	v_mul_f32_e32 v214, v198, v214
	v_mul_f32_e32 v215, v199, v215
	v_mul_f32_e32 v216, v200, v216
	v_mul_f32_e32 v217, v201, v217
	v_mul_f32_e32 v218, v202, v218
	v_mul_f32_e32 v219, v203, v219
	v_mul_f32_e32 v212, v204, v212
	v_mul_f32_e32 v213, v205, v213
	v_mul_f32_e32 v214, v206, v214
; __device__ __forceinline__ unsigned cvt_pk_bf16(float lo, float hi) { unsigned r; asm volatile("v_cvt_pk_bf16_f32 %0, %1, %2" : "=v"(r) : "v"(lo), "v"(hi)); return r; }
;     __device__ __forceinline__ void operator()(const f32x4 (&acc)[2][2][4][2], const Unit& u, int wr, int wc, int fr, int fq) const {
;     ...
;             for (int m = 0; m < 4; ++m) { const int row = row0 + ai * HALF + m * 16; const float rs = __builtin_amdgcn_rsqf((float)sq[ai][m] * (1.0f / (1024.0f * 1048576.0f)) + RMS_EPS);
;                 float hv[8];
; #pragma unroll
;                 for (int n = 0; n < 2; ++n)
; #pragma unroll
;                     for (int j = 0; j < 4; ++j) { const float g = acc[ai][0][m][n][j] * rs, uu = acc[ai][1][m][n][j] * rs;
;                         const float sg = g * __builtin_amdgcn_rcpf(1.0f + __builtin_amdgcn_exp2f(-1.4426950408889634f * g)); hv[n * 4 + j] = sg * uu; }
;                 u32x4 w; w.x = cvt_pk_bf16(hv[0], hv[1]); w.y = cvt_pk_bf16(hv[2], hv[3]); w.z = cvt_pk_bf16(hv[4], hv[5]); w.w = cvt_pk_bf16(hv[6], hv[7]);
;                 *(u32x4*)(H + (size_t)row * 2816 + col0) = w; }
	v_mul_f32_e32 v215, v207, v215
	v_mul_f32_e32 v216, v208, v216
	v_mul_f32_e32 v217, v209, v217
	v_mul_f32_e32 v218, v210, v218
	v_mul_f32_e32 v219, v211, v219
	v_mad_i64_i32 v[184:185], s[16:17], v160, s9, v[180:181]
	v_cvt_pk_bf16_f32 v188, v212, v213
	v_cvt_pk_bf16_f32 v189, v214, v215
	v_cvt_pk_bf16_f32 v190, v216, v217
	v_cvt_pk_bf16_f32 v191, v218, v219
	v_lshl_add_u64 v[184:185], v[184:185], 0, v[182:183]
	global_store_dwordx4 v[184:185], v[188:191], off
	v_mul_f32_e32 v196, v110, v173
	v_mul_f32_e32 v197, v111, v173
	v_mul_f32_e32 v198, v112, v173
	v_mul_f32_e32 v199, v113, v173
	v_mul_f32_e32 v200, v102, v173
	v_mul_f32_e32 v201, v103, v173
	v_mul_f32_e32 v202, v104, v173
	v_mul_f32_e32 v203, v105, v173
	v_mul_f32_e32 v204, v106, v173
	v_mul_f32_e32 v205, v107, v173
	v_mul_f32_e32 v206, v108, v173
	v_mul_f32_e32 v207, v109, v173
	v_mul_f32_e32 v208, v98, v173
	v_mul_f32_e32 v209, v99, v173
	v_mul_f32_e32 v210, v100, v173
	v_mul_f32_e32 v211, v101, v173
	v_mul_f32_e32 v212, 0xbfb8aa3b, v196
	v_mul_f32_e32 v213, 0xbfb8aa3b, v197
	v_mul_f32_e32 v214, 0xbfb8aa3b, v198
	v_mul_f32_e32 v215, 0xbfb8aa3b, v199
	v_mul_f32_e32 v216, 0xbfb8aa3b, v200
	v_mul_f32_e32 v217, 0xbfb8aa3b, v201
	v_mul_f32_e32 v218, 0xbfb8aa3b, v202
	v_mul_f32_e32 v219, 0xbfb8aa3b, v203
	v_exp_f32_e32 v212, v212
	v_exp_f32_e32 v213, v213
	v_exp_f32_e32 v214, v214
	v_exp_f32_e32 v215, v215
	v_exp_f32_e32 v216, v216
	v_exp_f32_e32 v217, v217
	v_exp_f32_e32 v218, v218
	v_exp_f32_e32 v219, v219
	v_add_f32_e32 v212, 1.0, v212
	v_add_f32_e32 v213, 1.0, v213
	v_add_f32_e32 v214, 1.0, v214
	v_add_f32_e32 v215, 1.0, v215
	v_add_f32_e32 v216, 1.0, v216
	v_add_f32_e32 v217, 1.0, v217
	v_add_f32_e32 v218, 1.0, v218
	v_add_f32_e32 v219, 1.0, v219
	v_rcp_f32_e32 v212, v212
	v_rcp_f32_e32 v213, v213
	v_rcp_f32_e32 v214, v214
	v_rcp_f32_e32 v215, v215
	v_rcp_f32_e32 v216, v216
	v_rcp_f32_e32 v217, v217
	v_rcp_f32_e32 v218, v218
	v_rcp_f32_e32 v219, v219
	v_mul_f32_e32 v212, v196, v212
	v_mul_f32_e32 v213, v197, v213
	v_mul_f32_e32 v214, v198, v214
	v_mul_f32_e32 v215, v199, v215
	v_mul_f32_e32 v216, v200, v216
	v_mul_f32_e32 v217, v201, v217
	v_mul_f32_e32 v218, v202, v218
	v_mul_f32_e32 v219, v203, v219
	v_mul_f32_e32 v212, v204, v212
	v_mul_f32_e32 v213, v205, v213
	v_mul_f32_e32 v214, v206, v214
	v_mul_f32_e32 v215, v207, v215
	v_mul_f32_e32 v216, v208, v216
	v_mul_f32_e32 v217, v209, v217
	v_mul_f32_e32 v218, v210, v218
	v_mul_f32_e32 v219, v211, v219
	v_mad_i64_i32 v[186:187], s[16:17], v156, s9, v[180:181]
	v_cvt_pk_bf16_f32 v192, v212, v213
	v_cvt_pk_bf16_f32 v193, v214, v215
	v_cvt_pk_bf16_f32 v194, v216, v217
	v_cvt_pk_bf16_f32 v195, v218, v219
	v_lshl_add_u64 v[186:187], v[186:187], 0, v[182:183]
	global_store_dwordx4 v[186:187], v[192:195], off
	v_mul_f32_e32 v196, v94, v174
	v_mul_f32_e32 v197, v95, v174
	v_mul_f32_e32 v198, v96, v174
	v_mul_f32_e32 v199, v97, v174
	v_mul_f32_e32 v200, v86, v174
	v_mul_f32_e32 v201, v87, v174
	v_mul_f32_e32 v202, v88, v174
	v_mul_f32_e32 v203, v89, v174
	v_mul_f32_e32 v204, v90, v174
	v_mul_f32_e32 v205, v91, v174
	v_mul_f32_e32 v206, v92, v174
	v_mul_f32_e32 v207, v93, v174
	v_mul_f32_e32 v208, v82, v174
	v_mul_f32_e32 v209, v83, v174
	v_mul_f32_e32 v210, v84, v174
	v_mul_f32_e32 v211, v85, v174
	v_mul_f32_e32 v212, 0xbfb8aa3b, v196
	v_mul_f32_e32 v213, 0xbfb8aa3b, v197
	v_mul_f32_e32 v214, 0xbfb8aa3b, v198
	v_mul_f32_e32 v215, 0xbfb8aa3b, v199
	v_mul_f32_e32 v216, 0xbfb8aa3b, v200
	v_mul_f32_e32 v217, 0xbfb8aa3b, v201
	v_mul_f32_e32 v218, 0xbfb8aa3b, v202
	v_mul_f32_e32 v219, 0xbfb8aa3b, v203
	v_exp_f32_e32 v212, v212
	v_exp_f32_e32 v213, v213
	v_exp_f32_e32 v214, v214
	v_exp_f32_e32 v215, v215
	v_exp_f32_e32 v216, v216
	v_exp_f32_e32 v217, v217
	v_exp_f32_e32 v218, v218
	v_exp_f32_e32 v219, v219
	v_add_f32_e32 v212, 1.0, v212
	v_add_f32_e32 v213, 1.0, v213
	v_add_f32_e32 v214, 1.0, v214
	v_add_f32_e32 v215, 1.0, v215
	v_add_f32_e32 v216, 1.0, v216
	v_add_f32_e32 v217, 1.0, v217
	v_add_f32_e32 v218, 1.0, v218
	v_add_f32_e32 v219, 1.0, v219
	v_rcp_f32_e32 v212, v212
	v_rcp_f32_e32 v213, v213
	v_rcp_f32_e32 v214, v214
	v_rcp_f32_e32 v215, v215
	v_rcp_f32_e32 v216, v216
	v_rcp_f32_e32 v217, v217
	v_rcp_f32_e32 v218, v218
	v_rcp_f32_e32 v219, v219
	v_mul_f32_e32 v212, v196, v212
	v_mul_f32_e32 v213, v197, v213
	v_mul_f32_e32 v214, v198, v214
	v_mul_f32_e32 v215, v199, v215
	v_mul_f32_e32 v216, v200, v216
	v_mul_f32_e32 v217, v201, v217
	v_mul_f32_e32 v218, v202, v218
	v_mul_f32_e32 v219, v203, v219
	v_mul_f32_e32 v212, v204, v212
	v_mul_f32_e32 v213, v205, v213
	v_mul_f32_e32 v214, v206, v214
	v_mul_f32_e32 v215, v207, v215
	v_mul_f32_e32 v216, v208, v216
	v_mul_f32_e32 v217, v209, v217
	v_mul_f32_e32 v218, v210, v218
	v_mul_f32_e32 v219, v211, v219
	v_mad_i64_i32 v[184:185], s[16:17], v152, s9, v[180:181]
	v_cvt_pk_bf16_f32 v188, v212, v213
	v_cvt_pk_bf16_f32 v189, v214, v215
	v_cvt_pk_bf16_f32 v190, v216, v217
	v_cvt_pk_bf16_f32 v191, v218, v219
	v_lshl_add_u64 v[184:185], v[184:185], 0, v[182:183]
	global_store_dwordx4 v[184:185], v[188:191], off
	v_mul_f32_e32 v196, v78, v175
	v_mul_f32_e32 v197, v79, v175
	v_mul_f32_e32 v198, v80, v175
	v_mul_f32_e32 v199, v81, v175
	v_mul_f32_e32 v200, v70, v175
	v_mul_f32_e32 v201, v71, v175
	v_mul_f32_e32 v202, v72, v175
	v_mul_f32_e32 v203, v73, v175
	v_mul_f32_e32 v204, v74, v175
	v_mul_f32_e32 v205, v75, v175
	v_mul_f32_e32 v206, v76, v175
	v_mul_f32_e32 v207, v77, v175
	v_mul_f32_e32 v208, v66, v175
	v_mul_f32_e32 v209, v67, v175
	v_mul_f32_e32 v210, v68, v175
	v_mul_f32_e32 v211, v69, v175
	v_mul_f32_e32 v212, 0xbfb8aa3b, v196
	v_mul_f32_e32 v213, 0xbfb8aa3b, v197
	v_mul_f32_e32 v214, 0xbfb8aa3b, v198
; __device__ __forceinline__ unsigned cvt_pk_bf16(float lo, float hi) { unsigned r; asm volatile("v_cvt_pk_bf16_f32 %0, %1, %2" : "=v"(r) : "v"(lo), "v"(hi)); return r; }
;     __device__ __forceinline__ void operator()(const f32x4 (&acc)[2][2][4][2], const Unit& u, int wr, int wc, int fr, int fq) const {
;     ...
;             for (int m = 0; m < 4; ++m) { const int row = row0 + ai * HALF + m * 16; const float rs = __builtin_amdgcn_rsqf((float)sq[ai][m] * (1.0f / (1024.0f * 1048576.0f)) + RMS_EPS);
;                 float hv[8];
; #pragma unroll
;                 for (int n = 0; n < 2; ++n)
; #pragma unroll
;                     for (int j = 0; j < 4; ++j) { const float g = acc[ai][0][m][n][j] * rs, uu = acc[ai][1][m][n][j] * rs;
;                         const float sg = g * __builtin_amdgcn_rcpf(1.0f + __builtin_amdgcn_exp2f(-1.4426950408889634f * g)); hv[n * 4 + j] = sg * uu; }
;                 u32x4 w; w.x = cvt_pk_bf16(hv[0], hv[1]); w.y = cvt_pk_bf16(hv[2], hv[3]); w.z = cvt_pk_bf16(hv[4], hv[5]); w.w = cvt_pk_bf16(hv[6], hv[7]);
;                 *(u32x4*)(H + (size_t)row * 2816 + col0) = w; }
	v_mul_f32_e32 v215, 0xbfb8aa3b, v199
	v_mul_f32_e32 v216, 0xbfb8aa3b, v200
	v_mul_f32_e32 v217, 0xbfb8aa3b, v201
	v_mul_f32_e32 v218, 0xbfb8aa3b, v202
	v_mul_f32_e32 v219, 0xbfb8aa3b, v203
	v_exp_f32_e32 v212, v212
	v_exp_f32_e32 v213, v213
	v_exp_f32_e32 v214, v214
	v_exp_f32_e32 v215, v215
	v_exp_f32_e32 v216, v216
	v_exp_f32_e32 v217, v217
	v_exp_f32_e32 v218, v218
	v_exp_f32_e32 v219, v219
	v_add_f32_e32 v212, 1.0, v212
	v_add_f32_e32 v213, 1.0, v213
	v_add_f32_e32 v214, 1.0, v214
	v_add_f32_e32 v215, 1.0, v215
	v_add_f32_e32 v216, 1.0, v216
	v_add_f32_e32 v217, 1.0, v217
	v_add_f32_e32 v218, 1.0, v218
	v_add_f32_e32 v219, 1.0, v219
	v_rcp_f32_e32 v212, v212
	v_rcp_f32_e32 v213, v213
	v_rcp_f32_e32 v214, v214
	v_rcp_f32_e32 v215, v215
	v_rcp_f32_e32 v216, v216
	v_rcp_f32_e32 v217, v217
	v_rcp_f32_e32 v218, v218
	v_rcp_f32_e32 v219, v219
	v_mul_f32_e32 v212, v196, v212
	v_mul_f32_e32 v213, v197, v213
	v_mul_f32_e32 v214, v198, v214
	v_mul_f32_e32 v215, v199, v215
	v_mul_f32_e32 v216, v200, v216
	v_mul_f32_e32 v217, v201, v217
	v_mul_f32_e32 v218, v202, v218
	v_mul_f32_e32 v219, v203, v219
	v_mul_f32_e32 v212, v204, v212
	v_mul_f32_e32 v213, v205, v213
	v_mul_f32_e32 v214, v206, v214
	v_mul_f32_e32 v215, v207, v215
	v_mul_f32_e32 v216, v208, v216
	v_mul_f32_e32 v217, v209, v217
	v_mul_f32_e32 v218, v210, v218
	v_mul_f32_e32 v219, v211, v219
	v_mad_i64_i32 v[186:187], s[16:17], v148, s9, v[180:181]
	v_cvt_pk_bf16_f32 v192, v212, v213
	v_cvt_pk_bf16_f32 v193, v214, v215
	v_cvt_pk_bf16_f32 v194, v216, v217
	v_cvt_pk_bf16_f32 v195, v218, v219
	v_lshl_add_u64 v[186:187], v[186:187], 0, v[182:183]
	global_store_dwordx4 v[186:187], v[192:195], off
	v_mul_f32_e32 v196, v62, v176
	v_mul_f32_e32 v197, v63, v176
	v_mul_f32_e32 v198, v64, v176
	v_mul_f32_e32 v199, v65, v176
	v_mul_f32_e32 v200, v54, v176
	v_mul_f32_e32 v201, v55, v176
	v_mul_f32_e32 v202, v56, v176
	v_mul_f32_e32 v203, v57, v176
	v_mul_f32_e32 v204, v58, v176
	v_mul_f32_e32 v205, v59, v176
	v_mul_f32_e32 v206, v60, v176
	v_mul_f32_e32 v207, v61, v176
	v_mul_f32_e32 v208, v50, v176
	v_mul_f32_e32 v209, v51, v176
	v_mul_f32_e32 v210, v52, v176
	v_mul_f32_e32 v211, v53, v176
	v_mul_f32_e32 v212, 0xbfb8aa3b, v196
	v_mul_f32_e32 v213, 0xbfb8aa3b, v197
	v_mul_f32_e32 v214, 0xbfb8aa3b, v198
	v_mul_f32_e32 v215, 0xbfb8aa3b, v199
	v_mul_f32_e32 v216, 0xbfb8aa3b, v200
	v_mul_f32_e32 v217, 0xbfb8aa3b, v201
	v_mul_f32_e32 v218, 0xbfb8aa3b, v202
	v_mul_f32_e32 v219, 0xbfb8aa3b, v203
	v_exp_f32_e32 v212, v212
	v_exp_f32_e32 v213, v213
	v_exp_f32_e32 v214, v214
	v_exp_f32_e32 v215, v215
	v_exp_f32_e32 v216, v216
	v_exp_f32_e32 v217, v217
	v_exp_f32_e32 v218, v218
	v_exp_f32_e32 v219, v219
	v_add_f32_e32 v212, 1.0, v212
	v_add_f32_e32 v213, 1.0, v213
	v_add_f32_e32 v214, 1.0, v214
	v_add_f32_e32 v215, 1.0, v215
	v_add_f32_e32 v216, 1.0, v216
	v_add_f32_e32 v217, 1.0, v217
	v_add_f32_e32 v218, 1.0, v218
	v_add_f32_e32 v219, 1.0, v219
	v_rcp_f32_e32 v212, v212
	v_rcp_f32_e32 v213, v213
	v_rcp_f32_e32 v214, v214
	v_rcp_f32_e32 v215, v215
	v_rcp_f32_e32 v216, v216
	v_rcp_f32_e32 v217, v217
	v_rcp_f32_e32 v218, v218
	v_rcp_f32_e32 v219, v219
	v_mul_f32_e32 v212, v196, v212
	v_mul_f32_e32 v213, v197, v213
	v_mul_f32_e32 v214, v198, v214
	v_mul_f32_e32 v215, v199, v215
	v_mul_f32_e32 v216, v200, v216
	v_mul_f32_e32 v217, v201, v217
	v_mul_f32_e32 v218, v202, v218
	v_mul_f32_e32 v219, v203, v219
	v_mul_f32_e32 v212, v204, v212
	v_mul_f32_e32 v213, v205, v213
	v_mul_f32_e32 v214, v206, v214
	v_mul_f32_e32 v215, v207, v215
	v_mul_f32_e32 v216, v208, v216
	v_mul_f32_e32 v217, v209, v217
	v_mul_f32_e32 v218, v210, v218
	v_mul_f32_e32 v219, v211, v219
	v_mad_i64_i32 v[184:185], s[16:17], v161, s9, v[180:181]
	v_cvt_pk_bf16_f32 v188, v212, v213
	v_cvt_pk_bf16_f32 v189, v214, v215
	v_cvt_pk_bf16_f32 v190, v216, v217
	v_cvt_pk_bf16_f32 v191, v218, v219
	v_lshl_add_u64 v[184:185], v[184:185], 0, v[182:183]
	global_store_dwordx4 v[184:185], v[188:191], off
	v_mul_f32_e32 v196, v46, v177
	v_mul_f32_e32 v197, v47, v177
	v_mul_f32_e32 v198, v48, v177
	v_mul_f32_e32 v199, v49, v177
	v_mul_f32_e32 v200, v38, v177
	v_mul_f32_e32 v201, v39, v177
	v_mul_f32_e32 v202, v40, v177
	v_mul_f32_e32 v203, v41, v177
	v_mul_f32_e32 v204, v42, v177
	v_mul_f32_e32 v205, v43, v177
	v_mul_f32_e32 v206, v44, v177
	v_mul_f32_e32 v207, v45, v177
	v_mul_f32_e32 v208, v34, v177
	v_mul_f32_e32 v209, v35, v177
	v_mul_f32_e32 v210, v36, v177
	v_mul_f32_e32 v211, v37, v177
	v_mul_f32_e32 v212, 0xbfb8aa3b, v196
	v_mul_f32_e32 v213, 0xbfb8aa3b, v197
	v_mul_f32_e32 v214, 0xbfb8aa3b, v198
	v_mul_f32_e32 v215, 0xbfb8aa3b, v199
	v_mul_f32_e32 v216, 0xbfb8aa3b, v200
	v_mul_f32_e32 v217, 0xbfb8aa3b, v201
	v_mul_f32_e32 v218, 0xbfb8aa3b, v202
	v_mul_f32_e32 v219, 0xbfb8aa3b, v203
	v_exp_f32_e32 v212, v212
	v_exp_f32_e32 v213, v213
	v_exp_f32_e32 v214, v214
	v_exp_f32_e32 v215, v215
	v_exp_f32_e32 v216, v216
	v_exp_f32_e32 v217, v217
	v_exp_f32_e32 v218, v218
	v_exp_f32_e32 v219, v219
	v_add_f32_e32 v212, 1.0, v212
	v_add_f32_e32 v213, 1.0, v213
	v_add_f32_e32 v214, 1.0, v214
	v_add_f32_e32 v215, 1.0, v215
	v_add_f32_e32 v216, 1.0, v216
	v_add_f32_e32 v217, 1.0, v217
	v_add_f32_e32 v218, 1.0, v218
	v_add_f32_e32 v219, 1.0, v219
	v_rcp_f32_e32 v212, v212
	v_rcp_f32_e32 v213, v213
	v_rcp_f32_e32 v214, v214
	v_rcp_f32_e32 v215, v215
	v_rcp_f32_e32 v216, v216
	v_rcp_f32_e32 v217, v217
	v_rcp_f32_e32 v218, v218
	v_rcp_f32_e32 v219, v219
	v_mul_f32_e32 v212, v196, v212
	v_mul_f32_e32 v213, v197, v213
; __device__ __forceinline__ unsigned cvt_pk_bf16(float lo, float hi) { unsigned r; asm volatile("v_cvt_pk_bf16_f32 %0, %1, %2" : "=v"(r) : "v"(lo), "v"(hi)); return r; }
; #define PG8_BAR __builtin_amdgcn_s_barrier()
;     __device__ __forceinline__ void operator()(const f32x4 (&acc)[2][2][4][2], const Unit& u, int wr, int wc, int fr, int fq) const {
;     ...
;             for (int m = 0; m < 4; ++m) { const int row = row0 + ai * HALF + m * 16; const float rs = __builtin_amdgcn_rsqf((float)sq[ai][m] * (1.0f / (1024.0f * 1048576.0f)) + RMS_EPS);
;                 float hv[8];
; #pragma unroll
;                 for (int n = 0; n < 2; ++n)
; #pragma unroll
;                     for (int j = 0; j < 4; ++j) { const float g = acc[ai][0][m][n][j] * rs, uu = acc[ai][1][m][n][j] * rs;
;                         const float sg = g * __builtin_amdgcn_rcpf(1.0f + __builtin_amdgcn_exp2f(-1.4426950408889634f * g)); hv[n * 4 + j] = sg * uu; }
;                 u32x4 w; w.x = cvt_pk_bf16(hv[0], hv[1]); w.y = cvt_pk_bf16(hv[2], hv[3]); w.z = cvt_pk_bf16(hv[4], hv[5]); w.w = cvt_pk_bf16(hv[6], hv[7]);
;                 *(u32x4*)(H + (size_t)row * 2816 + col0) = w; }
; template <class Epi, class Sched, bool ALIGN_EPI = false, bool SP2 = false>
; __device__ __forceinline__ void gemm_phase(PG8_LAS unsigned char* lds, const Gemm g, const Sched& S, const Epi& E, const int wv) {
;     ...
;         if constexpr (!Epi::AFTER_DRAIN) { E(acc, cur, wr, wc, fr, fq); S.done(cur); }
;         if (!has_next) break;
; #pragma unroll
;         for (int a = 0; a < 2; ++a)
; #pragma unroll
;             for (int b = 0; b < 2; ++b)
; #pragma unroll
;                 for (int m = 0; m < 4; ++m)
; #pragma unroll
;                     for (int n = 0; n < 2; ++n) acc[a][b][m][n] = (f32x4){0.f, 0.f, 0.f, 0.f};
;         cur = nxt; cA = nA; cB = nB; ++ui;
;         if constexpr (ALIGN_EPI) { if (wr == 1) PG8_BAR; }
	v_mul_f32_e32 v214, v198, v214
	v_mul_f32_e32 v215, v199, v215
	v_mul_f32_e32 v216, v200, v216
	v_mul_f32_e32 v217, v201, v217
	v_mul_f32_e32 v218, v202, v218
	v_mul_f32_e32 v219, v203, v219
	v_mul_f32_e32 v212, v204, v212
	v_mul_f32_e32 v213, v205, v213
	v_mul_f32_e32 v214, v206, v214
	v_mul_f32_e32 v215, v207, v215
	v_mul_f32_e32 v216, v208, v216
	v_mul_f32_e32 v217, v209, v217
	v_mul_f32_e32 v218, v210, v218
	v_mul_f32_e32 v219, v211, v219
	v_mad_i64_i32 v[186:187], s[16:17], v157, s9, v[180:181]
	v_cvt_pk_bf16_f32 v192, v212, v213
	v_cvt_pk_bf16_f32 v193, v214, v215
	v_cvt_pk_bf16_f32 v194, v216, v217
	v_cvt_pk_bf16_f32 v195, v218, v219
	v_lshl_add_u64 v[186:187], v[186:187], 0, v[182:183]
	global_store_dwordx4 v[186:187], v[192:195], off
	v_mul_f32_e32 v196, v30, v178
	v_mul_f32_e32 v197, v31, v178
	v_mul_f32_e32 v198, v32, v178
	v_mul_f32_e32 v199, v33, v178
	v_mul_f32_e32 v200, v22, v178
	v_mul_f32_e32 v201, v23, v178
	v_mul_f32_e32 v202, v24, v178
	v_mul_f32_e32 v203, v25, v178
	v_mul_f32_e32 v204, v26, v178
	v_mul_f32_e32 v205, v27, v178
	v_mul_f32_e32 v206, v28, v178
	v_mul_f32_e32 v207, v29, v178
	v_mul_f32_e32 v208, v18, v178
	v_mul_f32_e32 v209, v19, v178
	v_mul_f32_e32 v210, v20, v178
	v_mul_f32_e32 v211, v21, v178
	v_mul_f32_e32 v212, 0xbfb8aa3b, v196
	v_mul_f32_e32 v213, 0xbfb8aa3b, v197
	v_mul_f32_e32 v214, 0xbfb8aa3b, v198
	v_mul_f32_e32 v215, 0xbfb8aa3b, v199
	v_mul_f32_e32 v216, 0xbfb8aa3b, v200
	v_mul_f32_e32 v217, 0xbfb8aa3b, v201
	v_mul_f32_e32 v218, 0xbfb8aa3b, v202
	v_mul_f32_e32 v219, 0xbfb8aa3b, v203
	v_exp_f32_e32 v212, v212
	v_exp_f32_e32 v213, v213
	v_exp_f32_e32 v214, v214
	v_exp_f32_e32 v215, v215
	v_exp_f32_e32 v216, v216
	v_exp_f32_e32 v217, v217
	v_exp_f32_e32 v218, v218
	v_exp_f32_e32 v219, v219
	v_add_f32_e32 v212, 1.0, v212
	v_add_f32_e32 v213, 1.0, v213
	v_add_f32_e32 v214, 1.0, v214
	v_add_f32_e32 v215, 1.0, v215
	v_add_f32_e32 v216, 1.0, v216
	v_add_f32_e32 v217, 1.0, v217
	v_add_f32_e32 v218, 1.0, v218
	v_add_f32_e32 v219, 1.0, v219
	v_rcp_f32_e32 v212, v212
	v_rcp_f32_e32 v213, v213
	v_rcp_f32_e32 v214, v214
	v_rcp_f32_e32 v215, v215
	v_rcp_f32_e32 v216, v216
	v_rcp_f32_e32 v217, v217
	v_rcp_f32_e32 v218, v218
	v_rcp_f32_e32 v219, v219
	v_mul_f32_e32 v212, v196, v212
	v_mul_f32_e32 v213, v197, v213
	v_mul_f32_e32 v214, v198, v214
	v_mul_f32_e32 v215, v199, v215
	v_mul_f32_e32 v216, v200, v216
	v_mul_f32_e32 v217, v201, v217
	v_mul_f32_e32 v218, v202, v218
	v_mul_f32_e32 v219, v203, v219
	v_mul_f32_e32 v212, v204, v212
	v_mul_f32_e32 v213, v205, v213
	v_mul_f32_e32 v214, v206, v214
	v_mul_f32_e32 v215, v207, v215
	v_mul_f32_e32 v216, v208, v216
	v_mul_f32_e32 v217, v209, v217
	v_mul_f32_e32 v218, v210, v218
	v_mul_f32_e32 v219, v211, v219
	v_mad_i64_i32 v[184:185], s[16:17], v153, s9, v[180:181]
	v_cvt_pk_bf16_f32 v188, v212, v213
	v_cvt_pk_bf16_f32 v189, v214, v215
	v_cvt_pk_bf16_f32 v190, v216, v217
	v_cvt_pk_bf16_f32 v191, v218, v219
	v_lshl_add_u64 v[184:185], v[184:185], 0, v[182:183]
	global_store_dwordx4 v[184:185], v[188:191], off
	v_mul_f32_e32 v196, v14, v179
	v_mul_f32_e32 v197, v15, v179
	v_mul_f32_e32 v198, v16, v179
	v_mul_f32_e32 v199, v17, v179
	v_mul_f32_e32 v200, v6, v179
	v_mul_f32_e32 v201, v7, v179
	v_mul_f32_e32 v202, v8, v179
	v_mul_f32_e32 v203, v9, v179
	v_mul_f32_e32 v204, v10, v179
	v_mul_f32_e32 v205, v11, v179
	v_mul_f32_e32 v206, v12, v179
	v_mul_f32_e32 v207, v13, v179
	v_mul_f32_e32 v208, v2, v179
	v_mul_f32_e32 v209, v3, v179
	v_mul_f32_e32 v210, v4, v179
	v_mul_f32_e32 v211, v5, v179
	v_mul_f32_e32 v212, 0xbfb8aa3b, v196
	v_mul_f32_e32 v213, 0xbfb8aa3b, v197
	v_mul_f32_e32 v214, 0xbfb8aa3b, v198
	v_mul_f32_e32 v215, 0xbfb8aa3b, v199
	v_mul_f32_e32 v216, 0xbfb8aa3b, v200
	v_mul_f32_e32 v217, 0xbfb8aa3b, v201
	v_mul_f32_e32 v218, 0xbfb8aa3b, v202
	v_mul_f32_e32 v219, 0xbfb8aa3b, v203
	v_exp_f32_e32 v212, v212
	v_exp_f32_e32 v213, v213
	v_exp_f32_e32 v214, v214
	v_exp_f32_e32 v215, v215
	v_exp_f32_e32 v216, v216
	v_exp_f32_e32 v217, v217
	v_exp_f32_e32 v218, v218
	v_exp_f32_e32 v219, v219
	v_add_f32_e32 v212, 1.0, v212
	v_add_f32_e32 v213, 1.0, v213
	v_add_f32_e32 v214, 1.0, v214
	v_add_f32_e32 v215, 1.0, v215
	v_add_f32_e32 v216, 1.0, v216
	v_add_f32_e32 v217, 1.0, v217
	v_add_f32_e32 v218, 1.0, v218
	v_add_f32_e32 v219, 1.0, v219
	v_rcp_f32_e32 v212, v212
	v_rcp_f32_e32 v213, v213
	v_rcp_f32_e32 v214, v214
	v_rcp_f32_e32 v215, v215
	v_rcp_f32_e32 v216, v216
	v_rcp_f32_e32 v217, v217
	v_rcp_f32_e32 v218, v218
	v_rcp_f32_e32 v219, v219
	v_mul_f32_e32 v212, v196, v212
	v_mul_f32_e32 v213, v197, v213
	v_mul_f32_e32 v214, v198, v214
	v_mul_f32_e32 v215, v199, v215
	v_mul_f32_e32 v216, v200, v216
	v_mul_f32_e32 v217, v201, v217
	v_mul_f32_e32 v218, v202, v218
	v_mul_f32_e32 v219, v203, v219
	v_mul_f32_e32 v212, v204, v212
	v_mul_f32_e32 v213, v205, v213
	v_mul_f32_e32 v214, v206, v214
	v_mul_f32_e32 v215, v207, v215
	v_mul_f32_e32 v216, v208, v216
	v_mul_f32_e32 v217, v209, v217
	v_mul_f32_e32 v218, v210, v218
	v_mul_f32_e32 v219, v211, v219
	v_mad_i64_i32 v[186:187], s[16:17], v149, s9, v[180:181]
	v_cvt_pk_bf16_f32 v192, v212, v213
	v_cvt_pk_bf16_f32 v193, v214, v215
	v_cvt_pk_bf16_f32 v194, v216, v217
	v_cvt_pk_bf16_f32 v195, v218, v219
	v_lshl_add_u64 v[186:187], v[186:187], 0, v[182:183]
	s_mov_b64 s[16:17], -1
	global_store_dwordx4 v[186:187], v[192:195], off
	s_nop 0
	s_cbranch_vccnz .LBB0_424
	s_andn2_b64 vcc, exec, s[0:1]
	s_cbranch_vccnz .LBB0_423
	s_barrier
	s_branch .LBB0_423
